# v43 + norm1: the 192 four-row blocks of rows 32768.. (a fifth block, with the partial-sum fold in layer 1, for 24 workgroups) deferred to two waves each of 96 short-item workgroups of group 0's prep p
# speedup vs baseline: 1.0095x; 1.0095x over previous
; DI void norm_phase(float* X, const float* gain, bf16_t* XN, const float* wsm, float* SM, int wave, int lane, const float* part = nullptr) {
;     ...
;     if (wsm) { for (int row0 = gw * 4; row0 < MTOT; row0 += NGW * 4) norm_rows<4>(X, gv, XN, wsm, SM, row0, lane, part); }
; DI void prep_phase(PARAMS P, int l, int g, LAS unsigned char* lds, int wave, int lane) {
;     ...
;         __syncthreads();
;     }
; }
.LBB0_754:
	v_readlane_b32 s86, v254, 14
	v_readlane_b32 s36, v254, 18
	v_readlane_b32 s78, v254, 20
	v_readlane_b32 s68, v254, 24
	v_readlane_b32 s82, v254, 13
	v_readlane_b32 s87, v254, 15
	v_readlane_b32 s83, v254, 16
	v_readlane_b32 s90, v254, 17
	v_readlane_b32 s37, v254, 19
	v_readlane_b32 s79, v254, 21
	s_movk_i32 s91, 0x1600
	s_movk_i32 s64, 0x2210
	s_mov_b64 s[18:19], s[72:73]
	v_readlane_b32 s69, v254, 25
	s_cmp_lg_u32 s92, 0x100
	s_cbranch_scc1 .Lprep_non1
	s_cmp_lg_u32 s34, 0
	s_cbranch_scc1 .Lprep_non1
	s_bitcmp0_b32 s82, 0
	s_cbranch_scc0 .Lprep_non1
	s_add_i32 s100, s82, -18
	s_cmp_gt_u32 s100, 0xbe
	s_cbranch_scc1 .Lprep_non1
	s_mov_b32 s100, 1
	s_branch .Ln1_go

; #define BIDX bid_opaque()
; #define GDIM gdim_opaque()
; DI void norm_phase(float* X, const float* gain, bf16_t* XN, const float* wsm, float* SM, int wave, int lane, const float* part = nullptr) {
;     const int gw = BIDX * 8 + wave, NGW = GDIM * 8;
;     f32x4 gv[4];
; #pragma unroll
;     for (int j = 0; j < 4; ++j) gv[j] = ((const f32x4*)gain)[lane + 64 * j];
;     if (wsm) { for (int row0 = gw * 4; row0 < MTOT; row0 += NGW * 4) norm_rows<4>(X, gv, XN, wsm, SM, row0, lane, part); }
;     else { for (int row = gw; row < MTOT; row += NGW) norm_rows<1>(X, gv, XN, nullptr, nullptr, row, lane, part); }
.LBB0_940:
	s_andn2_b64 vcc, exec, s[8:9]
	s_cbranch_vccnz .LBB0_964
	s_mov_b32 s100, 0
.Ln1_go:
	s_waitcnt vmcnt(0)
	v_mov_b32_e32 v0, v228
	v_mov_b32_e32 v1, v228
	s_nop 0
	v_readfirstlane_b32 s0, v1
	s_ashr_i32 s1, s0, 6
	s_mov_b32 s0, s82
	s_lshl_b32 s2, s0, 3
	s_add_i32 s1, s2, s1
	s_load_dwordx2 s[10:11], s[18:19], 0xf0
	s_and_b32 s3, s1, 7
	s_mul_i32 s4, s96, 0x2400000
	v_and_b32_e32 v2, 63, v228
	v_lshlrev_b32_e32 v2, 4, v2
	s_lshl_b32 s3, s3, 10
	v_add_u32_e32 v2, s3, v2
	s_waitcnt lgkmcnt(0)
	s_add_u32 s10, s10, s4
	s_addc_u32 s11, s11, 0
	s_add_u32 s10, s10, 0xe860000
	s_addc_u32 s11, s11, 0
	s_add_i32 m0, s3, 0
	s_nop 0
	global_load_lds_dwordx4 v2, s[10:11]
	v_add_u32_e32 v2, 0x2000, v2
	s_add_i32 m0, s3, 8192
	s_nop 0
	global_load_lds_dwordx4 v2, s[10:11]
	v_add_u32_e32 v2, 0x2000, v2
	s_add_i32 m0, s3, 16384
	s_nop 0
	global_load_lds_dwordx4 v2, s[10:11]
	v_add_u32_e32 v2, 0x2000, v2
	s_add_i32 m0, s3, 24576
	s_nop 0
	global_load_lds_dwordx4 v2, s[10:11]
	v_add_u32_e32 v2, 0x2000, v2
	s_add_i32 m0, s3, 32768
	s_nop 0
	global_load_lds_dwordx4 v2, s[10:11]
	v_add_u32_e32 v2, 0x2000, v2
	s_add_i32 m0, s3, 40960
	s_nop 0
	global_load_lds_dwordx4 v2, s[10:11]
	v_add_u32_e32 v2, 0x2000, v2
	s_add_i32 m0, s3, 49152
	s_nop 0
	global_load_lds_dwordx4 v2, s[10:11]
	v_add_u32_e32 v2, 0x2000, v2
	s_add_i32 m0, s3, 57344
	s_nop 0
	global_load_lds_dwordx4 v2, s[10:11]
	v_add_u32_e32 v2, 0x2000, v2
	s_add_i32 m0, s3, 65536
	s_nop 0
	global_load_lds_dwordx4 v2, s[10:11]
	v_add_u32_e32 v2, 0x2000, v2
	s_add_i32 m0, s3, 73728
	s_nop 0
	global_load_lds_dwordx4 v2, s[10:11]
	v_add_u32_e32 v2, 0x2000, v2
	s_add_i32 m0, s3, 81920
	s_nop 0
	global_load_lds_dwordx4 v2, s[10:11]
	v_add_u32_e32 v2, 0x2000, v2
	s_add_i32 m0, s3, 90112
	s_nop 0
	global_load_lds_dwordx4 v2, s[10:11]
	v_add_u32_e32 v2, 0x2000, v2
	s_waitcnt vmcnt(0)
	s_barrier
	s_mov_b32 s0, s92
	s_cmp_eq_u32 s100, 1
	s_cbranch_scc1 .Ln1_defer
	s_movk_i32 s2, 0x20bf
	s_cmp_lg_u32 s92, 0x100
	s_cbranch_scc1 .Ln1_chk
	s_movk_i32 s2, 0x1fff
.Ln1_chk:
	s_cmp_gt_i32 s1, s2
	s_cbranch_scc1 .LBB0_964
	s_branch .Ln1_rng_done
.Ln1_defer:
	s_and_b32 s2, s1, 7
	s_cmp_gt_u32 s2, 1
	s_cbranch_scc1 .LBB0_964
	s_add_i32 s3, s82, -18
	s_lshr_b32 s3, s3, 1
	s_mul_i32 s2, s2, 0x60
	s_add_i32 s2, s2, s3
	s_add_i32 s1, s2, 0x2000
.Ln1_rng_done:
	s_cmp_lg_u32 s1, s1
	s_cbranch_scc1 .LBB0_964
	s_load_dwordx2 s[2:3], s[18:19], 0x48
	s_load_dwordx2 s[10:11], s[18:19], 0xf0
	s_cmp_gt_i32 s96, 0
	s_cselect_b64 s[8:9], -1, 0
	s_lshl_b32 s4, s96, 10
	s_ashr_i32 s5, s4, 31
	s_lshl_b64 s[4:5], s[4:5], 2
	s_waitcnt lgkmcnt(0)
	s_add_u32 s2, s2, s4
	v_and_b32_e32 v18, 63, v0
	s_addc_u32 s3, s3, s5
	v_lshlrev_b32_e32 v32, 4, v18
	global_load_dwordx4 v[0:3], v32, s[2:3]
	global_load_dwordx4 v[4:7], v32, s[2:3] offset:1024
	global_load_dwordx4 v[8:11], v32, s[2:3] offset:2048
	global_load_dwordx4 v[12:15], v32, s[2:3] offset:3072
	v_lshlrev_b32_e32 v16, 2, v18
	v_mov_b32_e32 v17, v33
	v_lshl_add_u64 v[16:17], s[10:11], 0, v[16:17]
	s_mov_b64 s[2:3], 0x10c80000
	v_lshl_add_u64 v[34:35], v[16:17], 0, s[2:3]
	v_lshl_add_u64 v[36:37], s[10:11], 0, v[32:33]
	s_mov_b64 s[2:3], 0x1c67a000
	v_lshlrev_b32_e32 v16, 3, v18
	v_mov_b32_e32 v17, v33
	s_mul_i32 s12, s96, 0x2400000
	s_lshl_b32 s6, s1, 2
	s_lshl_b32 s0, s0, 5
	v_lshl_add_u64 v[38:39], v[36:37], 0, s[2:3]
	v_lshl_add_u64 v[16:17], s[10:11], 0, v[16:17]
	s_mov_b64 s[2:3], 0x8300000
	s_mul_hi_i32 s7, s96, 0x2400000
	v_lshl_add_u64 v[40:41], v[16:17], 0, s[2:3]
	s_add_u32 s2, s10, s12
	s_addc_u32 s3, s11, s7
	v_cmp_gt_u32_e64 s[4:5], 32, v18
	v_lshlrev_b32_e32 v42, 12, v18
	v_lshl_add_u64 v[44:45], s[2:3], 0, v[32:33]
	s_xor_b64 s[8:9], s[8:9], -1
	s_load_dwordx2 s[98:99], s[18:19], 0x0
	s_waitcnt lgkmcnt(0)
	v_lshl_add_u64 v[186:187], s[98:99], 0, v[32:33]
	s_mov_b32 s101, 0x82ff
	s_cmp_eq_u32 s100, 1
	s_cbranch_scc0 .Ln1_nostride
	s_mov_b32 s0, 0x8000
	s_branch .Ln1_lim_done
.Ln1_nostride:
	s_cmp_lg_u32 s92, 0x100
	s_cbranch_scc1 .Ln1_lim_done
	s_movk_i32 s101, 0x7fff

; DI void norm_phase(float* X, const float* gain, bf16_t* XN, const float* wsm, float* SM, int wave, int lane, const float* part = nullptr) {
;     ...
;     if (wsm) { for (int row0 = gw * 4; row0 < MTOT; row0 += NGW * 4) norm_rows<4>(X, gv, XN, wsm, SM, row0, lane, part); }
.LBB0_943:
	s_or_b64 exec, exec, s[20:21]
	s_add_i32 s6, s6, s0
	s_cmp_gt_i32 s6, s101
	s_cbranch_scc1 .LBB0_964
